# barrier 11 (ATT1 to WO1) replaced by per-row-block O-rows-done counters (16 units each); GU1 additionally waits for a global ATT1-done counter because U overlays Q/K/V
# speedup vs baseline: 1.0303x; 1.0021x over previous
.LBB0_1120:
	s_waitcnt vmcnt(0)
	s_barrier
	s_mov_b64 s[6:7], exec
	v_readlane_b32 s0, v219, 25
	v_readlane_b32 s1, v219, 26
	s_and_b64 s[0:1], s[6:7], s[0:1]
	s_mov_b64 exec, s[0:1]
	s_cbranch_execz .LBB0_1172
	v_readlane_b32 s0, v219, 27
	v_readlane_b32 s1, v219, 28
	v_readlane_b32 s2, v219, 30
	s_waitcnt vmcnt(0) lgkmcnt(0)
	buffer_inv sc1
	s_bfe_u32 s3, s2, 0x10002
	s_lshl_b32 s3, s3, 3
	s_bfe_u32 s10, s2, 0x30004
	s_add_i32 s3, s3, s10
	s_add_i32 s3, s3, 16
	s_lshl_b32 s3, s3, 7
	s_add_i32 s3, s3, 0x60
	s_lshr_b32 s10, s2, 4
	s_lshl_b32 s10, s10, 7
	s_add_i32 s10, s10, 0x60
	s_and_b32 s11, s2, 31
	s_lshl_b32 s11, s11, 7
	s_add_i32 s11, s11, 0x60
	v_mov_b32_e32 v0, 1
	v_mov_b32_e32 v1, s3
	v_mov_b32_e32 v2, s10
	s_nop 1
	global_atomic_add v1, v0, s[0:1]
	global_atomic_add v2, v0, s[0:1]
	v_mov_b32_e32 v2, 0x1140
	s_nop 1
	global_atomic_add v2, v0, s[0:1]
	v_mov_b32_e32 v1, s11
	s_mov_b32 s15, 0

.LBB0_1293:
	s_or_b64 exec, exec, s[6:7]
	s_waitcnt vmcnt(0)
	s_barrier
	s_mov_b64 s[6:7], exec
	v_readlane_b32 s0, v219, 25
	v_readlane_b32 s1, v219, 26
	s_and_b64 s[0:1], s[6:7], s[0:1]
	s_mov_b64 exec, s[0:1]
	s_cbranch_execz .LBB0_1345
	v_readlane_b32 s0, v219, 27
	v_readlane_b32 s1, v219, 28
	v_readlane_b32 s2, v219, 30
	s_waitcnt vmcnt(0) lgkmcnt(0)
	buffer_inv sc1
	s_and_b32 s3, s2, 31
	s_lshl_b32 s3, s3, 7
	s_add_i32 s3, s3, 64
	v_mov_b32_e32 v1, s3
	v_mov_b32_e32 v0, 1
	s_nop 1
	global_atomic_add v1, v0, s[0:1]
	s_mov_b32 s15, 0
	v_mov_b32_e32 v0, 0x1140
.Lgb13_spin:
	global_load_dword v2, v1, s[0:1] sc1
	global_load_dword v0, v0, s[0:1] sc1
	s_waitcnt vmcnt(0)
	v_readfirstlane_b32 s13, v2
	v_readfirstlane_b32 s14, v0
	v_mov_b32_e32 v0, 0x1140
	s_nop 1
	s_cmp_lt_u32 s13, 56
	s_cbranch_scc1 .Lgb13_again
	s_cmp_lt_u32 s14, 256
	s_cbranch_scc1 .Lgb13_again
	s_branch .Lgb13_done
